# grid barriers after P1/P4/P6/P9: the first arriver of each XCD issues an early L2 write-back (not waited for) so the leader's release write-back has less to do
# baseline (speedup 1.0000x reference)
; __device__ __forceinline__ unsigned xb_ld(unsigned* p)              { return __hip_atomic_load(p, __ATOMIC_RELAXED, __HIP_MEMORY_SCOPE_AGENT); }
; __device__ __forceinline__ unsigned xb_add(unsigned* p, unsigned v) { return __hip_atomic_fetch_add(p, v, __ATOMIC_RELAXED, __HIP_MEMORY_SCOPE_AGENT); }
; #define XB_SPIN(cond, bar) do { unsigned _sp = 0; while (cond) { __builtin_amdgcn_s_sleep(1); \
;     if ((++_sp & 255u) == 0u) { if (xb_ld(&(bar)[XB_TMO])) break; if (_sp > XB_SPIN_CAP) { atomicAdd(&(bar)[XB_TMO], 1u); break; } } } } while (0)
; __device__ __forceinline__ void xcd_barrier(const XcdBarrier& b) {
;     asm volatile("s_waitcnt vmcnt(0)" ::: "memory");
;     __syncthreads();
;     if (threadIdx.x == 0) {
;         unsigned* bar = b.bar;
;         __builtin_amdgcn_s_waitcnt(0);
;         unsigned nloc = b.st[0], nx = b.st[1];
;         if (nloc == 0u) { xcd_barrier_complete(bar, b.x, nloc, nx); b.st[0] = nloc; b.st[1] = nx; }
;         const unsigned old = xb_add(&bar[XB_XSUB(b.x)], 1u);
;         const unsigned gen = old / nloc;
;         if (old + 1u == (gen + 1u) * nloc) {
;             __builtin_amdgcn_fence(__ATOMIC_RELEASE, "agent");
;             asm volatile("s_waitcnt vmcnt(0)" ::: "memory");
;             const unsigned og = xb_add(&bar[XB_TOP], 1u);
;             const unsigned tg = og / nx;
;             if (og + 1u == (tg + 1u) * nx) xb_add(&bar[XB_TOPGEN], 1u);
;             else XB_SPIN(xb_ld(&bar[XB_TOPGEN]) == tg, bar);
;             __builtin_amdgcn_fence(__ATOMIC_ACQUIRE, "agent");
;             xb_add(&bar[XB_XGEN(b.x)], 1u);
;             asm volatile("s_waitcnt vmcnt(0)" ::: "memory");
;         } else {
;             XB_SPIN(xb_ld(&bar[XB_XGEN(b.x)]) == gen, bar);
.LBB0_134:
	s_or_b64 exec, exec, s[6:7]
	v_cvt_f32_u32_e32 v5, v3
	s_waitcnt vmcnt(0)
	v_readfirstlane_b32 s2, v4
	v_sub_u32_e32 v4, 0, v3
	v_rcp_iflag_f32_e32 v5, v5
	v_add_u32_e32 v6, s2, v2
	v_mul_f32_e32 v5, 0x4f7ffffe, v5
	v_cvt_u32_f32_e32 v5, v5
	v_mul_lo_u32 v2, v4, v5
	v_mul_hi_u32 v2, v5, v2
	v_add_u32_e32 v2, v5, v2
	v_mul_hi_u32 v2, v6, v2
	v_mul_lo_u32 v4, v2, v3
	v_sub_u32_e32 v4, v6, v4
	v_add_u32_e32 v5, 1, v2
	v_cmp_ge_u32_e32 vcc, v4, v3
	s_nop 1
	v_cndmask_b32_e32 v2, v2, v5, vcc
	v_sub_u32_e32 v5, v4, v3
	v_cndmask_b32_e32 v4, v4, v5, vcc
	v_add_u32_e32 v5, 1, v2
	v_cmp_ge_u32_e32 vcc, v4, v3
	v_add_u32_e32 v4, 1, v6
	s_nop 0
	v_cndmask_b32_e32 v2, v2, v5, vcc
	v_mul_lo_u32 v5, v3, v2
	v_add_u32_e32 v3, v5, v3
	v_cmp_ne_u32_e32 vcc, v4, v3
	s_and_saveexec_b64 s[2:3], vcc
	s_xor_b64 s[2:3], exec, s[2:3]
	s_cbranch_execz .LBB0_148
	s_waitcnt lgkmcnt(0)
	v_cmp_eq_u32_e32 vcc, v6, v5
	s_cbranch_vccz .Lnoearlyflush1
	buffer_wbl2 sc1
.Lnoearlyflush1:
	v_mov_b32_e32 v255, 0x23f64
	ds_read_b32 v254, v255
	v_mov_b32_e32 v1, 0
	s_add_u32 s12, s54, 0x7400
	s_addc_u32 s13, s55, 0
	global_load_dword v1, v1, s[12:13] sc1
	s_waitcnt lgkmcnt(0)
	v_mad_u32_u24 v254, v2, v254, v254
	s_waitcnt vmcnt(0)
	v_cmp_lt_u32_e32 vcc, v1, v254
	s_and_saveexec_b64 s[6:7], vcc
	s_cbranch_execz .LBB0_147
	s_add_u32 s10, s54, 0x4200
	s_addc_u32 s11, s55, 0
	s_mov_b32 s26, 1
	s_mov_b64 s[14:15], 0
	v_mov_b32_e32 v1, 0
	s_branch .LBB0_138

; __device__ __forceinline__ unsigned xb_ld(unsigned* p)              { return __hip_atomic_load(p, __ATOMIC_RELAXED, __HIP_MEMORY_SCOPE_AGENT); }
; __device__ __forceinline__ unsigned xb_add(unsigned* p, unsigned v) { return __hip_atomic_fetch_add(p, v, __ATOMIC_RELAXED, __HIP_MEMORY_SCOPE_AGENT); }
; #define XB_SPIN(cond, bar) do { unsigned _sp = 0; while (cond) { __builtin_amdgcn_s_sleep(1); \
;     if ((++_sp & 255u) == 0u) { if (xb_ld(&(bar)[XB_TMO])) break; if (_sp > XB_SPIN_CAP) { atomicAdd(&(bar)[XB_TMO], 1u); break; } } } } while (0)
; __device__ __forceinline__ void xcd_barrier(const XcdBarrier& b) {
;     ...
;         const unsigned old = xb_add(&bar[XB_XSUB(b.x)], 1u);
;         const unsigned gen = old / nloc;
;         if (old + 1u == (gen + 1u) * nloc) {
;             __builtin_amdgcn_fence(__ATOMIC_RELEASE, "agent");
;             asm volatile("s_waitcnt vmcnt(0)" ::: "memory");
;             const unsigned og = xb_add(&bar[XB_TOP], 1u);
;             const unsigned tg = og / nx;
;             if (og + 1u == (tg + 1u) * nx) xb_add(&bar[XB_TOPGEN], 1u);
;             else XB_SPIN(xb_ld(&bar[XB_TOPGEN]) == tg, bar);
;             __builtin_amdgcn_fence(__ATOMIC_ACQUIRE, "agent");
;             xb_add(&bar[XB_XGEN(b.x)], 1u);
;             asm volatile("s_waitcnt vmcnt(0)" ::: "memory");
;         } else {
;             XB_SPIN(xb_ld(&bar[XB_XGEN(b.x)]) == gen, bar);
.Lnoearlyflush3:
	v_mov_b32_e32 v255, 0x23f64
	ds_read_b32 v254, v255
	v_mov_b32_e32 v1, 0
	v_readlane_b32 s10, v244, 24
	v_readlane_b32 s11, v244, 25
	s_nop 1
	s_add_u32 s10, s10, 0x7400
	s_addc_u32 s11, s11, 0
	global_load_dword v1, v1, s[10:11] sc1
	s_waitcnt lgkmcnt(0)
	v_mad_u32_u24 v254, v2, v254, v254
	s_waitcnt vmcnt(0)
	v_cmp_lt_u32_e32 vcc, v1, v254
	s_and_saveexec_b64 s[6:7], vcc
	s_cbranch_execz .LBB0_984
	v_readlane_b32 s8, v244, 24
	v_readlane_b32 s9, v244, 25
	s_add_u32 s8, s8, 0x4200
	s_addc_u32 s9, s9, 0
	s_mov_b32 s22, 1
	s_mov_b64 s[12:13], 0
	v_mov_b32_e32 v1, 0
	s_branch .LBB0_975

; __device__ __forceinline__ unsigned xb_ld(unsigned* p)              { return __hip_atomic_load(p, __ATOMIC_RELAXED, __HIP_MEMORY_SCOPE_AGENT); }
; __device__ __forceinline__ unsigned xb_add(unsigned* p, unsigned v) { return __hip_atomic_fetch_add(p, v, __ATOMIC_RELAXED, __HIP_MEMORY_SCOPE_AGENT); }
; #define XB_SPIN(cond, bar) do { unsigned _sp = 0; while (cond) { __builtin_amdgcn_s_sleep(1); \
;     if ((++_sp & 255u) == 0u) { if (xb_ld(&(bar)[XB_TMO])) break; if (_sp > XB_SPIN_CAP) { atomicAdd(&(bar)[XB_TMO], 1u); break; } } } } while (0)
; __device__ __forceinline__ void xcd_barrier(const XcdBarrier& b) {
;     ...
;         const unsigned old = xb_add(&bar[XB_XSUB(b.x)], 1u);
;         const unsigned gen = old / nloc;
;         if (old + 1u == (gen + 1u) * nloc) {
;             __builtin_amdgcn_fence(__ATOMIC_RELEASE, "agent");
;             asm volatile("s_waitcnt vmcnt(0)" ::: "memory");
;             const unsigned og = xb_add(&bar[XB_TOP], 1u);
;             const unsigned tg = og / nx;
;             if (og + 1u == (tg + 1u) * nx) xb_add(&bar[XB_TOPGEN], 1u);
;             else XB_SPIN(xb_ld(&bar[XB_TOPGEN]) == tg, bar);
;             __builtin_amdgcn_fence(__ATOMIC_ACQUIRE, "agent");
;             xb_add(&bar[XB_XGEN(b.x)], 1u);
;             asm volatile("s_waitcnt vmcnt(0)" ::: "memory");
;         } else {
;             XB_SPIN(xb_ld(&bar[XB_XGEN(b.x)]) == gen, bar);
.LBB0_1437:
	s_or_b64 exec, exec, s[6:7]
	v_cvt_f32_u32_e32 v6, v4
	s_waitcnt vmcnt(0)
	v_readfirstlane_b32 s2, v5
	v_sub_u32_e32 v5, 0, v4
	v_rcp_iflag_f32_e32 v6, v6
	v_add_u32_e32 v7, s2, v3
	v_mul_f32_e32 v6, 0x4f7ffffe, v6
	v_cvt_u32_f32_e32 v6, v6
	v_mul_lo_u32 v3, v5, v6
	v_mul_hi_u32 v3, v6, v3
	v_add_u32_e32 v3, v6, v3
	v_mul_hi_u32 v3, v7, v3
	v_mul_lo_u32 v5, v3, v4
	v_sub_u32_e32 v5, v7, v5
	v_add_u32_e32 v6, 1, v3
	v_cmp_ge_u32_e32 vcc, v5, v4
	s_nop 1
	v_cndmask_b32_e32 v3, v3, v6, vcc
	v_sub_u32_e32 v6, v5, v4
	v_cndmask_b32_e32 v5, v5, v6, vcc
	v_add_u32_e32 v6, 1, v3
	v_cmp_ge_u32_e32 vcc, v5, v4
	v_add_u32_e32 v5, 1, v7
	s_nop 0
	v_cndmask_b32_e32 v3, v3, v6, vcc
	v_mul_lo_u32 v6, v4, v3
	v_add_u32_e32 v4, v6, v4
	v_cmp_ne_u32_e32 vcc, v5, v4
	s_and_saveexec_b64 s[2:3], vcc
	s_xor_b64 s[2:3], exec, s[2:3]
	s_cbranch_execz .LBB0_1453
	s_waitcnt lgkmcnt(0)
	v_cmp_eq_u32_e32 vcc, v7, v6
	s_cbranch_vccz .Lnoearlyflush5
	buffer_wbl2 sc1
.Lnoearlyflush5:
	v_mov_b32_e32 v255, 0x23f64
	ds_read_b32 v254, v255
	v_mov_b32_e32 v2, 0
	s_add_u32 s10, s54, 0x7400
	s_addc_u32 s11, s55, 0
	global_load_dword v2, v2, s[10:11] sc1
	s_waitcnt lgkmcnt(0)
	v_mad_u32_u24 v254, v3, v254, v254
	s_waitcnt vmcnt(0)
	v_cmp_lt_u32_e32 vcc, v2, v254
	s_and_saveexec_b64 s[6:7], vcc
	s_cbranch_execz .LBB0_1452
	s_add_u32 s8, s54, 0x4200
	s_addc_u32 s9, s55, 0
	s_mov_b32 s22, 1
	s_mov_b64 s[12:13], 0
	v_mov_b32_e32 v2, 0
	s_branch .LBB0_1441

; __device__ __forceinline__ unsigned xb_ld(unsigned* p)              { return __hip_atomic_load(p, __ATOMIC_RELAXED, __HIP_MEMORY_SCOPE_AGENT); }
; __device__ __forceinline__ unsigned xb_add(unsigned* p, unsigned v) { return __hip_atomic_fetch_add(p, v, __ATOMIC_RELAXED, __HIP_MEMORY_SCOPE_AGENT); }
; #define XB_SPIN(cond, bar) do { unsigned _sp = 0; while (cond) { __builtin_amdgcn_s_sleep(1); \
;     if ((++_sp & 255u) == 0u) { if (xb_ld(&(bar)[XB_TMO])) break; if (_sp > XB_SPIN_CAP) { atomicAdd(&(bar)[XB_TMO], 1u); break; } } } } while (0)
; __device__ __forceinline__ void xcd_barrier(const XcdBarrier& b) {
;     ...
;         const unsigned old = xb_add(&bar[XB_XSUB(b.x)], 1u);
;         const unsigned gen = old / nloc;
;         if (old + 1u == (gen + 1u) * nloc) {
;             __builtin_amdgcn_fence(__ATOMIC_RELEASE, "agent");
;             asm volatile("s_waitcnt vmcnt(0)" ::: "memory");
;             const unsigned og = xb_add(&bar[XB_TOP], 1u);
;             const unsigned tg = og / nx;
;             if (og + 1u == (tg + 1u) * nx) xb_add(&bar[XB_TOPGEN], 1u);
;             else XB_SPIN(xb_ld(&bar[XB_TOPGEN]) == tg, bar);
;             __builtin_amdgcn_fence(__ATOMIC_ACQUIRE, "agent");
;             xb_add(&bar[XB_XGEN(b.x)], 1u);
;             asm volatile("s_waitcnt vmcnt(0)" ::: "memory");
;         } else {
;             XB_SPIN(xb_ld(&bar[XB_XGEN(b.x)]) == gen, bar);
.LBB0_1653:
	s_or_b64 exec, exec, s[12:13]
	v_cvt_f32_u32_e32 v6, v4
	s_waitcnt vmcnt(0)
	v_readfirstlane_b32 s2, v5
	v_sub_u32_e32 v5, 0, v4
	v_rcp_iflag_f32_e32 v6, v6
	v_add_u32_e32 v7, s2, v3
	v_mul_f32_e32 v6, 0x4f7ffffe, v6
	v_cvt_u32_f32_e32 v6, v6
	v_mul_lo_u32 v3, v5, v6
	v_mul_hi_u32 v3, v6, v3
	v_add_u32_e32 v3, v6, v3
	v_mul_hi_u32 v3, v7, v3
	v_mul_lo_u32 v5, v3, v4
	v_sub_u32_e32 v5, v7, v5
	v_add_u32_e32 v6, 1, v3
	v_cmp_ge_u32_e32 vcc, v5, v4
	s_nop 1
	v_cndmask_b32_e32 v3, v3, v6, vcc
	v_sub_u32_e32 v6, v5, v4
	v_cndmask_b32_e32 v5, v5, v6, vcc
	v_add_u32_e32 v6, 1, v3
	v_cmp_ge_u32_e32 vcc, v5, v4
	v_add_u32_e32 v5, 1, v7
	s_nop 0
	v_cndmask_b32_e32 v3, v3, v6, vcc
	v_mul_lo_u32 v6, v4, v3
	v_add_u32_e32 v4, v6, v4
	v_cmp_ne_u32_e32 vcc, v5, v4
	s_and_saveexec_b64 s[2:3], vcc
	s_xor_b64 s[2:3], exec, s[2:3]
	s_cbranch_execz .LBB0_1667
	s_waitcnt lgkmcnt(0)
	v_cmp_eq_u32_e32 vcc, v7, v6
	s_cbranch_vccz .Lnoearlyflush7
	buffer_wbl2 sc1
.Lnoearlyflush7:
	v_mov_b32_e32 v255, 0x23f64
	ds_read_b32 v254, v255
	v_mov_b32_e32 v2, 0
	s_add_u32 s16, s54, 0x7400
	s_addc_u32 s17, s55, 0
	global_load_dword v2, v2, s[16:17] sc1
	s_waitcnt lgkmcnt(0)
	v_mad_u32_u24 v254, v3, v254, v254
	s_waitcnt vmcnt(0)
	v_cmp_lt_u32_e32 vcc, v2, v254
	s_and_saveexec_b64 s[12:13], vcc
	s_cbranch_execz .LBB0_1666
	s_add_u32 s14, s54, 0x4200
	s_addc_u32 s15, s55, 0
	s_mov_b32 s28, 1
	s_mov_b64 s[18:19], 0
	v_mov_b32_e32 v2, 0
	s_branch .LBB0_1657
